# grid barrier spin loops: s_sleep 1 removed from the 36 poll loops (polls are already paced by the sc1 load round trip)
# baseline (speedup 1.0000x reference)
.LBB0_77:
	global_load_dword v15, v16, s[4:5] sc1
	global_load_dword v0, v16, s[8:9] sc1
	global_load_dword v1, v16, s[14:15] sc1
	global_load_dword v2, v16, s[28:29] sc1
	global_load_dword v3, v16, s[30:31] sc1
	global_load_dword v4, v16, s[40:41] sc1
	global_load_dword v5, v16, s[42:43] sc1
	global_load_dword v6, v16, s[52:53] sc1
	global_load_dword v7, v16, s[54:55] sc1
	global_load_dword v8, v16, s[56:57] sc1
	global_load_dword v9, v16, s[58:59] sc1
	global_load_dword v10, v16, s[60:61] sc1
	global_load_dword v11, v16, s[62:63] sc1
	global_load_dword v12, v16, s[64:65] sc1
	global_load_dword v13, v16, s[66:67] sc1
	global_load_dword v14, v16, s[76:77] sc1
	s_mov_b64 s[78:79], -1
	s_mov_b64 s[80:81], -1
	s_waitcnt vmcnt(14)
	v_add_u32_e32 v17, v0, v15
	s_waitcnt vmcnt(13)
	v_add_u32_e32 v17, v17, v1
	s_waitcnt vmcnt(12)
	v_add_u32_e32 v17, v17, v2
	s_waitcnt vmcnt(11)
	v_add_u32_e32 v17, v17, v3
	s_waitcnt vmcnt(10)
	v_add_u32_e32 v17, v17, v4
	s_waitcnt vmcnt(9)
	v_add_u32_e32 v17, v17, v5
	s_waitcnt vmcnt(8)
	v_add_u32_e32 v17, v17, v6
	s_waitcnt vmcnt(7)
	v_add_u32_e32 v17, v17, v7
	s_waitcnt vmcnt(6)
	v_add_u32_e32 v17, v17, v8
	s_waitcnt vmcnt(5)
	v_add_u32_e32 v17, v17, v9
	s_waitcnt vmcnt(4)
	v_add_u32_e32 v17, v17, v10
	s_waitcnt vmcnt(3)
	v_add_u32_e32 v17, v17, v11
	s_waitcnt vmcnt(2)
	v_add_u32_e32 v17, v17, v12
	s_waitcnt vmcnt(1)
	v_add_u32_e32 v17, v17, v13
	s_waitcnt vmcnt(0)
	v_add_u32_e32 v17, v17, v14
	v_cmp_eq_u32_e32 vcc, s11, v17
	s_cbranch_vccnz .LBB0_76
	s_and_b32 s78, s35, 0xff
	s_cmp_eq_u32 s78, 0
	s_mov_b64 s[78:79], -1
	s_mov_b64 s[82:83], -1
	s_nop 0
	s_cbranch_scc1 .LBB0_81
	s_and_b64 vcc, exec, s[82:83]
	s_cbranch_vccz .LBB0_76

.LBB0_95:
	s_and_b32 s35, s11, 0xff
	s_mov_b64 s[42:43], -1
	s_cmp_lg_u32 s35, 0
	s_mov_b64 s[54:55], -1
	s_nop 0
	s_cbranch_scc0 .LBB0_98
	s_and_b64 vcc, exec, s[54:55]
	s_cbranch_vccz .LBB0_94

.LBB0_112:
	s_and_b32 s35, s11, 0xff
	s_cmp_lg_u32 s35, 0
	s_mov_b64 s[52:53], -1
	s_nop 0
	s_cbranch_scc0 .LBB0_115
	s_mov_b64 s[54:55], -1
	s_and_b64 vcc, exec, s[52:53]
	s_cbranch_vccz .LBB0_111

.LBB0_323:
	global_load_dword v15, v16, s[6:7] sc1
	global_load_dword v0, v16, s[8:9] sc1
	global_load_dword v1, v16, s[12:13] sc1
	global_load_dword v2, v16, s[16:17] sc1
	global_load_dword v3, v16, s[18:19] sc1
	global_load_dword v4, v16, s[20:21] sc1
	global_load_dword v5, v16, s[22:23] sc1
	global_load_dword v6, v16, s[28:29] sc1
	global_load_dword v7, v16, s[38:39] sc1
	global_load_dword v8, v16, s[48:49] sc1
	global_load_dword v9, v16, s[52:53] sc1
	global_load_dword v10, v16, s[54:55] sc1
	global_load_dword v11, v16, s[56:57] sc1
	global_load_dword v12, v16, s[58:59] sc1
	global_load_dword v13, v16, s[60:61] sc1
	global_load_dword v14, v16, s[62:63] sc1
	s_mov_b64 s[64:65], -1
	s_mov_b64 s[66:67], -1
	s_waitcnt vmcnt(14)
	v_add_u32_e32 v17, v0, v15
	s_waitcnt vmcnt(13)
	v_add_u32_e32 v17, v17, v1
	s_waitcnt vmcnt(12)
	v_add_u32_e32 v17, v17, v2
	s_waitcnt vmcnt(11)
	v_add_u32_e32 v17, v17, v3
	s_waitcnt vmcnt(10)
	v_add_u32_e32 v17, v17, v4
	s_waitcnt vmcnt(9)
	v_add_u32_e32 v17, v17, v5
	s_waitcnt vmcnt(8)
	v_add_u32_e32 v17, v17, v6
	s_waitcnt vmcnt(7)
	v_add_u32_e32 v17, v17, v7
	s_waitcnt vmcnt(6)
	v_add_u32_e32 v17, v17, v8
	s_waitcnt vmcnt(5)
	v_add_u32_e32 v17, v17, v9
	s_waitcnt vmcnt(4)
	v_add_u32_e32 v17, v17, v10
	s_waitcnt vmcnt(3)
	v_add_u32_e32 v17, v17, v11
	s_waitcnt vmcnt(2)
	v_add_u32_e32 v17, v17, v12
	s_waitcnt vmcnt(1)
	v_add_u32_e32 v17, v17, v13
	s_waitcnt vmcnt(0)
	v_add_u32_e32 v17, v17, v14
	v_cmp_eq_u32_e32 vcc, s11, v17
	s_cbranch_vccnz .LBB0_322
	s_and_b32 s15, s14, 0xff
	s_cmp_eq_u32 s15, 0
	s_mov_b64 s[76:77], -1
	s_nop 0
	s_cbranch_scc1 .LBB0_327
	s_and_b64 vcc, exec, s[76:77]
	s_cbranch_vccz .LBB0_322

.LBB0_341:
	s_and_b32 s14, s11, 0xff
	s_mov_b64 s[22:23], -1
	s_cmp_lg_u32 s14, 0
	s_mov_b64 s[38:39], -1
	s_nop 0
	s_cbranch_scc0 .LBB0_344
	s_and_b64 vcc, exec, s[38:39]
	s_cbranch_vccz .LBB0_340

.LBB0_358:
	s_and_b32 s14, s11, 0xff
	s_cmp_lg_u32 s14, 0
	s_mov_b64 s[28:29], -1
	s_nop 0
	s_cbranch_scc0 .LBB0_361
	s_mov_b64 s[38:39], -1
	s_and_b64 vcc, exec, s[28:29]
	s_cbranch_vccz .LBB0_357

.LBB0_572:
	global_load_dword v15, v16, s[8:9] sc1
	global_load_dword v0, v16, s[12:13] sc1
	global_load_dword v1, v16, s[16:17] sc1
	global_load_dword v2, v16, s[18:19] sc1
	global_load_dword v3, v16, s[20:21] sc1
	global_load_dword v4, v16, s[22:23] sc1
	global_load_dword v5, v16, s[28:29] sc1
	global_load_dword v6, v16, s[38:39] sc1
	global_load_dword v7, v16, s[46:47] sc1
	global_load_dword v8, v16, s[48:49] sc1
	global_load_dword v9, v16, s[50:51] sc1
	global_load_dword v10, v16, s[52:53] sc1
	global_load_dword v11, v16, s[54:55] sc1
	global_load_dword v12, v16, s[56:57] sc1
	global_load_dword v13, v16, s[58:59] sc1
	global_load_dword v14, v16, s[60:61] sc1
	s_mov_b64 s[62:63], -1
	s_mov_b64 s[64:65], -1
	s_waitcnt vmcnt(14)
	v_add_u32_e32 v17, v0, v15
	s_waitcnt vmcnt(13)
	v_add_u32_e32 v17, v17, v1
	s_waitcnt vmcnt(12)
	v_add_u32_e32 v17, v17, v2
	s_waitcnt vmcnt(11)
	v_add_u32_e32 v17, v17, v3
	s_waitcnt vmcnt(10)
	v_add_u32_e32 v17, v17, v4
	s_waitcnt vmcnt(9)
	v_add_u32_e32 v17, v17, v5
	s_waitcnt vmcnt(8)
	v_add_u32_e32 v17, v17, v6
	s_waitcnt vmcnt(7)
	v_add_u32_e32 v17, v17, v7
	s_waitcnt vmcnt(6)
	v_add_u32_e32 v17, v17, v8
	s_waitcnt vmcnt(5)
	v_add_u32_e32 v17, v17, v9
	s_waitcnt vmcnt(4)
	v_add_u32_e32 v17, v17, v10
	s_waitcnt vmcnt(3)
	v_add_u32_e32 v17, v17, v11
	s_waitcnt vmcnt(2)
	v_add_u32_e32 v17, v17, v12
	s_waitcnt vmcnt(1)
	v_add_u32_e32 v17, v17, v13
	s_waitcnt vmcnt(0)
	v_add_u32_e32 v17, v17, v14
	v_cmp_eq_u32_e32 vcc, s11, v17
	s_cbranch_vccnz .LBB0_571
	s_and_b32 s15, s14, 0xff
	s_cmp_eq_u32 s15, 0
	s_mov_b64 s[66:67], -1
	s_nop 0
	s_cbranch_scc1 .LBB0_576
	s_and_b64 vcc, exec, s[66:67]
	s_cbranch_vccz .LBB0_571

.LBB0_590:
	s_and_b32 s14, s11, 0xff
	s_mov_b64 s[28:29], -1
	s_cmp_lg_u32 s14, 0
	s_mov_b64 s[46:47], -1
	s_nop 0
	s_cbranch_scc0 .LBB0_593
	s_and_b64 vcc, exec, s[46:47]
	s_cbranch_vccz .LBB0_589

.LBB0_607:
	s_and_b32 s14, s11, 0xff
	s_cmp_lg_u32 s14, 0
	s_mov_b64 s[38:39], -1
	s_nop 0
	s_cbranch_scc0 .LBB0_610
	s_mov_b64 s[46:47], -1
	s_and_b64 vcc, exec, s[38:39]
	s_cbranch_vccz .LBB0_606

.LBB0_670:
	global_load_dword v15, v16, s[8:9] sc1
	global_load_dword v0, v16, s[16:17] sc1
	global_load_dword v1, v16, s[18:19] sc1
	global_load_dword v2, v16, s[20:21] sc1
	global_load_dword v3, v16, s[22:23] sc1
	global_load_dword v4, v16, s[28:29] sc1
	global_load_dword v5, v16, s[30:31] sc1
	global_load_dword v6, v16, s[38:39] sc1
	global_load_dword v7, v16, s[46:47] sc1
	global_load_dword v8, v16, s[48:49] sc1
	global_load_dword v9, v16, s[50:51] sc1
	global_load_dword v10, v16, s[52:53] sc1
	global_load_dword v11, v16, s[54:55] sc1
	global_load_dword v12, v16, s[56:57] sc1
	global_load_dword v13, v16, s[58:59] sc1
	global_load_dword v14, v16, s[60:61] sc1
	s_mov_b64 s[62:63], -1
	s_mov_b64 s[64:65], -1
	s_waitcnt vmcnt(14)
	v_add_u32_e32 v17, v0, v15
	s_waitcnt vmcnt(13)
	v_add_u32_e32 v17, v17, v1
	s_waitcnt vmcnt(12)
	v_add_u32_e32 v17, v17, v2
	s_waitcnt vmcnt(11)
	v_add_u32_e32 v17, v17, v3
	s_waitcnt vmcnt(10)
	v_add_u32_e32 v17, v17, v4
	s_waitcnt vmcnt(9)
	v_add_u32_e32 v17, v17, v5
	s_waitcnt vmcnt(8)
	v_add_u32_e32 v17, v17, v6
	s_waitcnt vmcnt(7)
	v_add_u32_e32 v17, v17, v7
	s_waitcnt vmcnt(6)
	v_add_u32_e32 v17, v17, v8
	s_waitcnt vmcnt(5)
	v_add_u32_e32 v17, v17, v9
	s_waitcnt vmcnt(4)
	v_add_u32_e32 v17, v17, v10
	s_waitcnt vmcnt(3)
	v_add_u32_e32 v17, v17, v11
	s_waitcnt vmcnt(2)
	v_add_u32_e32 v17, v17, v12
	s_waitcnt vmcnt(1)
	v_add_u32_e32 v17, v17, v13
	s_waitcnt vmcnt(0)
	v_add_u32_e32 v17, v17, v14
	v_cmp_eq_u32_e32 vcc, s11, v17
	s_cbranch_vccnz .LBB0_669
	s_and_b32 s15, s14, 0xff
	s_cmp_eq_u32 s15, 0
	s_mov_b64 s[66:67], -1
	s_nop 0
	s_cbranch_scc1 .LBB0_674
	s_and_b64 vcc, exec, s[66:67]
	s_cbranch_vccz .LBB0_669

.LBB0_688:
	s_and_b32 s14, s11, 0xff
	s_mov_b64 s[30:31], -1
	s_cmp_lg_u32 s14, 0
	s_mov_b64 s[46:47], -1
	s_nop 0
	s_cbranch_scc0 .LBB0_691
	s_and_b64 vcc, exec, s[46:47]
	s_cbranch_vccz .LBB0_687

.LBB0_732:
	global_load_dword v15, v16, s[8:9] sc1
	global_load_dword v0, v16, s[16:17] sc1
	global_load_dword v1, v16, s[18:19] sc1
	global_load_dword v2, v16, s[20:21] sc1
	global_load_dword v3, v16, s[22:23] sc1
	global_load_dword v4, v16, s[28:29] sc1
	global_load_dword v5, v16, s[30:31] sc1
	global_load_dword v6, v16, s[34:35] sc1
	global_load_dword v7, v16, s[38:39] sc1
	global_load_dword v8, v16, s[44:45] sc1
	global_load_dword v9, v16, s[46:47] sc1
	global_load_dword v10, v16, s[48:49] sc1
	global_load_dword v11, v16, s[50:51] sc1
	global_load_dword v12, v16, s[52:53] sc1
	global_load_dword v13, v16, s[54:55] sc1
	global_load_dword v14, v16, s[56:57] sc1
	s_mov_b64 s[58:59], -1
	s_mov_b64 s[60:61], -1
	s_waitcnt vmcnt(14)
	v_add_u32_e32 v17, v0, v15
	s_waitcnt vmcnt(13)
	v_add_u32_e32 v17, v17, v1
	s_waitcnt vmcnt(12)
	v_add_u32_e32 v17, v17, v2
	s_waitcnt vmcnt(11)
	v_add_u32_e32 v17, v17, v3
	s_waitcnt vmcnt(10)
	v_add_u32_e32 v17, v17, v4
	s_waitcnt vmcnt(9)
	v_add_u32_e32 v17, v17, v5
	s_waitcnt vmcnt(8)
	v_add_u32_e32 v17, v17, v6
	s_waitcnt vmcnt(7)
	v_add_u32_e32 v17, v17, v7
	s_waitcnt vmcnt(6)
	v_add_u32_e32 v17, v17, v8
	s_waitcnt vmcnt(5)
	v_add_u32_e32 v17, v17, v9
	s_waitcnt vmcnt(4)
	v_add_u32_e32 v17, v17, v10
	s_waitcnt vmcnt(3)
	v_add_u32_e32 v17, v17, v11
	s_waitcnt vmcnt(2)
	v_add_u32_e32 v17, v17, v12
	s_waitcnt vmcnt(1)
	v_add_u32_e32 v17, v17, v13
	s_waitcnt vmcnt(0)
	v_add_u32_e32 v17, v17, v14
	v_cmp_eq_u32_e32 vcc, s11, v17
	s_cbranch_vccnz .LBB0_731
	s_and_b32 s15, s14, 0xff
	s_cmp_eq_u32 s15, 0
	s_mov_b64 s[62:63], -1
	s_nop 0
	s_cbranch_scc1 .LBB0_736
	s_and_b64 vcc, exec, s[62:63]
	s_cbranch_vccz .LBB0_731

.LBB0_750:
	s_and_b32 s14, s11, 0xff
	s_mov_b64 s[30:31], -1
	s_cmp_lg_u32 s14, 0
	s_mov_b64 s[38:39], -1
	s_nop 0
	s_cbranch_scc0 .LBB0_753
	s_and_b64 vcc, exec, s[38:39]
	s_cbranch_vccz .LBB0_749

.LBB0_767:
	s_and_b32 s14, s11, 0xff
	s_cmp_lg_u32 s14, 0
	s_mov_b64 s[34:35], -1
	s_nop 0
	s_cbranch_scc0 .LBB0_770
	s_mov_b64 s[38:39], -1
	s_and_b64 vcc, exec, s[34:35]
	s_cbranch_vccz .LBB0_766

.LBB0_827:
	global_load_dword v15, v16, s[6:7] sc1
	global_load_dword v0, v16, s[8:9] sc1
	global_load_dword v1, v16, s[16:17] sc1
	global_load_dword v2, v16, s[18:19] sc1
	global_load_dword v3, v16, s[20:21] sc1
	global_load_dword v4, v16, s[22:23] sc1
	global_load_dword v5, v16, s[28:29] sc1
	global_load_dword v6, v16, s[30:31] sc1
	global_load_dword v7, v16, s[34:35] sc1
	global_load_dword v8, v16, s[38:39] sc1
	global_load_dword v9, v16, s[44:45] sc1
	global_load_dword v10, v16, s[46:47] sc1
	global_load_dword v11, v16, s[48:49] sc1
	global_load_dword v12, v16, s[50:51] sc1
	global_load_dword v13, v16, s[52:53] sc1
	global_load_dword v14, v16, s[54:55] sc1
	s_mov_b64 s[56:57], -1
	s_mov_b64 s[58:59], -1
	s_waitcnt vmcnt(14)
	v_add_u32_e32 v17, v0, v15
	s_waitcnt vmcnt(13)
	v_add_u32_e32 v17, v17, v1
	s_waitcnt vmcnt(12)
	v_add_u32_e32 v17, v17, v2
	s_waitcnt vmcnt(11)
	v_add_u32_e32 v17, v17, v3
	s_waitcnt vmcnt(10)
	v_add_u32_e32 v17, v17, v4
	s_waitcnt vmcnt(9)
	v_add_u32_e32 v17, v17, v5
	s_waitcnt vmcnt(8)
	v_add_u32_e32 v17, v17, v6
	s_waitcnt vmcnt(7)
	v_add_u32_e32 v17, v17, v7
	s_waitcnt vmcnt(6)
	v_add_u32_e32 v17, v17, v8
	s_waitcnt vmcnt(5)
	v_add_u32_e32 v17, v17, v9
	s_waitcnt vmcnt(4)
	v_add_u32_e32 v17, v17, v10
	s_waitcnt vmcnt(3)
	v_add_u32_e32 v17, v17, v11
	s_waitcnt vmcnt(2)
	v_add_u32_e32 v17, v17, v12
	s_waitcnt vmcnt(1)
	v_add_u32_e32 v17, v17, v13
	s_waitcnt vmcnt(0)
	v_add_u32_e32 v17, v17, v14
	v_cmp_eq_u32_e32 vcc, s11, v17
	s_cbranch_vccnz .LBB0_826
	s_and_b32 s15, s14, 0xff
	s_cmp_eq_u32 s15, 0
	s_mov_b64 s[60:61], -1
	s_nop 0
	s_cbranch_scc1 .LBB0_831
	s_and_b64 vcc, exec, s[60:61]
	s_cbranch_vccz .LBB0_826

.LBB0_845:
	s_and_b32 s14, s11, 0xff
	s_mov_b64 s[28:29], -1
	s_cmp_lg_u32 s14, 0
	s_mov_b64 s[34:35], -1
	s_nop 0
	s_cbranch_scc0 .LBB0_848
	s_and_b64 vcc, exec, s[34:35]
	s_cbranch_vccz .LBB0_844

.LBB0_862:
	s_and_b32 s14, s11, 0xff
	s_cmp_lg_u32 s14, 0
	s_mov_b64 s[30:31], -1
	s_nop 0
	s_cbranch_scc0 .LBB0_865
	s_mov_b64 s[34:35], -1
	s_and_b64 vcc, exec, s[30:31]
	s_cbranch_vccz .LBB0_861

.LBB0_920:
	global_load_dword v15, v16, s[6:7] sc1
	global_load_dword v0, v16, s[8:9] sc1
	global_load_dword v1, v16, s[18:19] sc1
	global_load_dword v2, v16, s[20:21] sc1
	global_load_dword v3, v16, s[22:23] sc1
	global_load_dword v4, v16, s[28:29] sc1
	global_load_dword v5, v16, s[30:31] sc1
	global_load_dword v6, v16, s[34:35] sc1
	global_load_dword v7, v16, s[36:37] sc1
	global_load_dword v8, v16, s[38:39] sc1
	global_load_dword v9, v16, s[44:45] sc1
	global_load_dword v10, v16, s[46:47] sc1
	global_load_dword v11, v16, s[48:49] sc1
	global_load_dword v12, v16, s[50:51] sc1
	global_load_dword v13, v16, s[52:53] sc1
	global_load_dword v14, v16, s[54:55] sc1
	s_mov_b64 s[56:57], -1
	s_mov_b64 s[58:59], -1
	s_waitcnt vmcnt(14)
	v_add_u32_e32 v17, v0, v15
	s_waitcnt vmcnt(13)
	v_add_u32_e32 v17, v17, v1
	s_waitcnt vmcnt(12)
	v_add_u32_e32 v17, v17, v2
	s_waitcnt vmcnt(11)
	v_add_u32_e32 v17, v17, v3
	s_waitcnt vmcnt(10)
	v_add_u32_e32 v17, v17, v4
	s_waitcnt vmcnt(9)
	v_add_u32_e32 v17, v17, v5
	s_waitcnt vmcnt(8)
	v_add_u32_e32 v17, v17, v6
	s_waitcnt vmcnt(7)
	v_add_u32_e32 v17, v17, v7
	s_waitcnt vmcnt(6)
	v_add_u32_e32 v17, v17, v8
	s_waitcnt vmcnt(5)
	v_add_u32_e32 v17, v17, v9
	s_waitcnt vmcnt(4)
	v_add_u32_e32 v17, v17, v10
	s_waitcnt vmcnt(3)
	v_add_u32_e32 v17, v17, v11
	s_waitcnt vmcnt(2)
	v_add_u32_e32 v17, v17, v12
	s_waitcnt vmcnt(1)
	v_add_u32_e32 v17, v17, v13
	s_waitcnt vmcnt(0)
	v_add_u32_e32 v17, v17, v14
	v_cmp_eq_u32_e32 vcc, s11, v17
	s_cbranch_vccnz .LBB0_919
	s_and_b32 s15, s14, 0xff
	s_cmp_eq_u32 s15, 0
	s_mov_b64 s[60:61], -1
	s_nop 0
	s_cbranch_scc1 .LBB0_924
	s_and_b64 vcc, exec, s[60:61]
	s_cbranch_vccz .LBB0_919

.LBB0_938:
	s_and_b32 s14, s11, 0xff
	s_mov_b64 s[30:31], -1
	s_cmp_lg_u32 s14, 0
	s_mov_b64 s[36:37], -1
	s_nop 0
	s_cbranch_scc0 .LBB0_941
	s_and_b64 vcc, exec, s[36:37]
	s_cbranch_vccz .LBB0_937

.LBB0_955:
	s_and_b32 s14, s11, 0xff
	s_cmp_lg_u32 s14, 0
	s_mov_b64 s[34:35], -1
	s_nop 0
	s_cbranch_scc0 .LBB0_958
	s_mov_b64 s[36:37], -1
	s_and_b64 vcc, exec, s[34:35]
	s_cbranch_vccz .LBB0_954

.LBB0_1008:
	global_load_dword v15, v16, s[6:7] sc1
	global_load_dword v0, v16, s[8:9] sc1
	global_load_dword v1, v16, s[20:21] sc1
	global_load_dword v2, v16, s[22:23] sc1
	global_load_dword v3, v16, s[28:29] sc1
	global_load_dword v4, v16, s[30:31] sc1
	global_load_dword v5, v16, s[34:35] sc1
	global_load_dword v6, v16, s[36:37] sc1
	global_load_dword v7, v16, s[38:39] sc1
	global_load_dword v8, v16, s[44:45] sc1
	global_load_dword v9, v16, s[46:47] sc1
	global_load_dword v10, v16, s[48:49] sc1
	global_load_dword v11, v16, s[50:51] sc1
	global_load_dword v12, v16, s[52:53] sc1
	global_load_dword v13, v16, s[54:55] sc1
	global_load_dword v14, v16, s[56:57] sc1
	s_mov_b64 s[58:59], -1
	s_mov_b64 s[60:61], -1
	s_waitcnt vmcnt(14)
	v_add_u32_e32 v17, v0, v15
	s_waitcnt vmcnt(13)
	v_add_u32_e32 v17, v17, v1
	s_waitcnt vmcnt(12)
	v_add_u32_e32 v17, v17, v2
	s_waitcnt vmcnt(11)
	v_add_u32_e32 v17, v17, v3
	s_waitcnt vmcnt(10)
	v_add_u32_e32 v17, v17, v4
	s_waitcnt vmcnt(9)
	v_add_u32_e32 v17, v17, v5
	s_waitcnt vmcnt(8)
	v_add_u32_e32 v17, v17, v6
	s_waitcnt vmcnt(7)
	v_add_u32_e32 v17, v17, v7
	s_waitcnt vmcnt(6)
	v_add_u32_e32 v17, v17, v8
	s_waitcnt vmcnt(5)
	v_add_u32_e32 v17, v17, v9
	s_waitcnt vmcnt(4)
	v_add_u32_e32 v17, v17, v10
	s_waitcnt vmcnt(3)
	v_add_u32_e32 v17, v17, v11
	s_waitcnt vmcnt(2)
	v_add_u32_e32 v17, v17, v12
	s_waitcnt vmcnt(1)
	v_add_u32_e32 v17, v17, v13
	s_waitcnt vmcnt(0)
	v_add_u32_e32 v17, v17, v14
	v_cmp_eq_u32_e32 vcc, s11, v17
	s_cbranch_vccnz .LBB0_1007
	s_and_b32 s15, s14, 0xff
	s_cmp_eq_u32 s15, 0
	s_mov_b64 s[62:63], -1
	s_nop 0
	s_cbranch_scc1 .LBB0_1012
	s_and_b64 vcc, exec, s[62:63]
	s_cbranch_vccz .LBB0_1007

.LBB0_1026:
	s_and_b32 s14, s11, 0xff
	s_mov_b64 s[34:35], -1
	s_cmp_lg_u32 s14, 0
	s_mov_b64 s[38:39], -1
	s_nop 0
	s_cbranch_scc0 .LBB0_1029
	s_and_b64 vcc, exec, s[38:39]
	s_cbranch_vccz .LBB0_1025

.LBB0_1043:
	s_and_b32 s14, s11, 0xff
	s_cmp_lg_u32 s14, 0
	s_mov_b64 s[36:37], -1
	s_nop 0
	s_cbranch_scc0 .LBB0_1046
	s_mov_b64 s[38:39], -1
	s_and_b64 vcc, exec, s[36:37]
	s_cbranch_vccz .LBB0_1042

.LBB0_1067:
	global_load_dword v15, v16, s[4:5] sc1
	global_load_dword v0, v16, s[6:7] sc1
	global_load_dword v1, v16, s[8:9] sc1
	global_load_dword v2, v16, s[20:21] sc1
	global_load_dword v3, v16, s[22:23] sc1
	global_load_dword v4, v16, s[24:25] sc1
	global_load_dword v5, v16, s[26:27] sc1
	global_load_dword v6, v16, s[28:29] sc1
	global_load_dword v7, v16, s[30:31] sc1
	global_load_dword v8, v16, s[34:35] sc1
	global_load_dword v9, v16, s[36:37] sc1
	global_load_dword v10, v16, s[38:39] sc1
	global_load_dword v11, v16, s[44:45] sc1
	global_load_dword v12, v16, s[46:47] sc1
	global_load_dword v13, v16, s[48:49] sc1
	global_load_dword v14, v16, s[50:51] sc1
	s_mov_b64 s[52:53], -1
	s_mov_b64 s[54:55], -1
	s_waitcnt vmcnt(14)
	v_add_u32_e32 v17, v0, v15
	s_waitcnt vmcnt(13)
	v_add_u32_e32 v17, v17, v1
	s_waitcnt vmcnt(12)
	v_add_u32_e32 v17, v17, v2
	s_waitcnt vmcnt(11)
	v_add_u32_e32 v17, v17, v3
	s_waitcnt vmcnt(10)
	v_add_u32_e32 v17, v17, v4
	s_waitcnt vmcnt(9)
	v_add_u32_e32 v17, v17, v5
	s_waitcnt vmcnt(8)
	v_add_u32_e32 v17, v17, v6
	s_waitcnt vmcnt(7)
	v_add_u32_e32 v17, v17, v7
	s_waitcnt vmcnt(6)
	v_add_u32_e32 v17, v17, v8
	s_waitcnt vmcnt(5)
	v_add_u32_e32 v17, v17, v9
	s_waitcnt vmcnt(4)
	v_add_u32_e32 v17, v17, v10
	s_waitcnt vmcnt(3)
	v_add_u32_e32 v17, v17, v11
	s_waitcnt vmcnt(2)
	v_add_u32_e32 v17, v17, v12
	s_waitcnt vmcnt(1)
	v_add_u32_e32 v17, v17, v13
	s_waitcnt vmcnt(0)
	v_add_u32_e32 v17, v17, v14
	v_cmp_eq_u32_e32 vcc, s11, v17
	s_cbranch_vccnz .LBB0_1066
	s_and_b32 s15, s14, 0xff
	s_cmp_eq_u32 s15, 0
	s_mov_b64 s[56:57], -1
	s_nop 0
	s_cbranch_scc1 .LBB0_1071
	s_and_b64 vcc, exec, s[56:57]
	s_cbranch_vccz .LBB0_1066

.LBB0_1085:
	s_and_b32 s14, s11, 0xff
	s_mov_b64 s[26:27], -1
	s_cmp_lg_u32 s14, 0
	s_mov_b64 s[30:31], -1
	s_nop 0
	s_cbranch_scc0 .LBB0_1088
	s_and_b64 vcc, exec, s[30:31]
	s_cbranch_vccz .LBB0_1084

.LBB0_1102:
	s_and_b32 s14, s11, 0xff
	s_cmp_lg_u32 s14, 0
	s_mov_b64 s[28:29], -1
	s_nop 0
	s_cbranch_scc0 .LBB0_1105
	s_mov_b64 s[30:31], -1
	s_and_b64 vcc, exec, s[28:29]
	s_cbranch_vccz .LBB0_1101

.LBB0_1192:
	global_load_dword v15, v16, s[6:7] sc1
	global_load_dword v0, v16, s[8:9] sc1
	global_load_dword v1, v16, s[20:21] sc1
	global_load_dword v2, v16, s[22:23] sc1
	global_load_dword v3, v16, s[24:25] sc1
	global_load_dword v4, v16, s[26:27] sc1
	global_load_dword v5, v16, s[28:29] sc1
	global_load_dword v6, v16, s[30:31] sc1
	global_load_dword v7, v16, s[34:35] sc1
	global_load_dword v8, v16, s[36:37] sc1
	global_load_dword v9, v16, s[38:39] sc1
	global_load_dword v10, v16, s[44:45] sc1
	global_load_dword v11, v16, s[46:47] sc1
	global_load_dword v12, v16, s[48:49] sc1
	global_load_dword v13, v16, s[50:51] sc1
	global_load_dword v14, v16, s[52:53] sc1
	s_mov_b64 s[54:55], -1
	s_mov_b64 s[56:57], -1
	s_waitcnt vmcnt(14)
	v_add_u32_e32 v17, v0, v15
	s_waitcnt vmcnt(13)
	v_add_u32_e32 v17, v17, v1
	s_waitcnt vmcnt(12)
	v_add_u32_e32 v17, v17, v2
	s_waitcnt vmcnt(11)
	v_add_u32_e32 v17, v17, v3
	s_waitcnt vmcnt(10)
	v_add_u32_e32 v17, v17, v4
	s_waitcnt vmcnt(9)
	v_add_u32_e32 v17, v17, v5
	s_waitcnt vmcnt(8)
	v_add_u32_e32 v17, v17, v6
	s_waitcnt vmcnt(7)
	v_add_u32_e32 v17, v17, v7
	s_waitcnt vmcnt(6)
	v_add_u32_e32 v17, v17, v8
	s_waitcnt vmcnt(5)
	v_add_u32_e32 v17, v17, v9
	s_waitcnt vmcnt(4)
	v_add_u32_e32 v17, v17, v10
	s_waitcnt vmcnt(3)
	v_add_u32_e32 v17, v17, v11
	s_waitcnt vmcnt(2)
	v_add_u32_e32 v17, v17, v12
	s_waitcnt vmcnt(1)
	v_add_u32_e32 v17, v17, v13
	s_waitcnt vmcnt(0)
	v_add_u32_e32 v17, v17, v14
	v_cmp_eq_u32_e32 vcc, s11, v17
	s_cbranch_vccnz .LBB0_1191
	s_and_b32 s15, s14, 0xff
	s_cmp_eq_u32 s15, 0
	s_mov_b64 s[58:59], -1
	s_nop 0
	s_cbranch_scc1 .LBB0_1196
	s_and_b64 vcc, exec, s[58:59]
	s_cbranch_vccz .LBB0_1191

.LBB0_1289:
	global_load_dword v15, v16, s[6:7] sc1
	global_load_dword v0, v16, s[8:9] sc1
	global_load_dword v1, v16, s[10:11] sc1
	global_load_dword v2, v16, s[12:13] sc1
	global_load_dword v3, v16, s[14:15] sc1
	global_load_dword v4, v16, s[16:17] sc1
	global_load_dword v5, v16, s[18:19] sc1
	global_load_dword v6, v16, s[20:21] sc1
	global_load_dword v7, v16, s[22:23] sc1
	global_load_dword v8, v16, s[24:25] sc1
	global_load_dword v9, v16, s[26:27] sc1
	global_load_dword v10, v16, s[28:29] sc1
	global_load_dword v11, v16, s[30:31] sc1
	global_load_dword v12, v16, s[34:35] sc1
	global_load_dword v13, v16, s[36:37] sc1
	global_load_dword v14, v16, s[38:39] sc1
	s_mov_b64 s[40:41], -1
	s_mov_b64 s[42:43], -1
	s_waitcnt vmcnt(14)
	v_add_u32_e32 v17, v0, v15
	s_waitcnt vmcnt(13)
	v_add_u32_e32 v17, v17, v1
	s_waitcnt vmcnt(12)
	v_add_u32_e32 v17, v17, v2
	s_waitcnt vmcnt(11)
	v_add_u32_e32 v17, v17, v3
	s_waitcnt vmcnt(10)
	v_add_u32_e32 v17, v17, v4
	s_waitcnt vmcnt(9)
	v_add_u32_e32 v17, v17, v5
	s_waitcnt vmcnt(8)
	v_add_u32_e32 v17, v17, v6
	s_waitcnt vmcnt(7)
	v_add_u32_e32 v17, v17, v7
	s_waitcnt vmcnt(6)
	v_add_u32_e32 v17, v17, v8
	s_waitcnt vmcnt(5)
	v_add_u32_e32 v17, v17, v9
	s_waitcnt vmcnt(4)
	v_add_u32_e32 v17, v17, v10
	s_waitcnt vmcnt(3)
	v_add_u32_e32 v17, v17, v11
	s_waitcnt vmcnt(2)
	v_add_u32_e32 v17, v17, v12
	s_waitcnt vmcnt(1)
	v_add_u32_e32 v17, v17, v13
	s_waitcnt vmcnt(0)
	v_add_u32_e32 v17, v17, v14
	v_cmp_eq_u32_e32 vcc, s46, v17
	s_cbranch_vccnz .LBB0_1288
	s_and_b32 s40, s47, 0xff
	s_cmp_eq_u32 s40, 0
	s_mov_b64 s[40:41], -1
	s_mov_b64 s[44:45], -1
	s_nop 0
	s_cbranch_scc1 .LBB0_1293
	s_and_b64 vcc, exec, s[44:45]
	s_cbranch_vccz .LBB0_1288

.LBB0_1307:
	s_and_b32 s20, s24, 0xff
	s_mov_b64 s[18:19], -1
	s_cmp_lg_u32 s20, 0
	s_mov_b64 s[22:23], -1
	s_nop 0
	s_cbranch_scc0 .LBB0_1310
	s_and_b64 vcc, exec, s[22:23]
	s_cbranch_vccz .LBB0_1306

.LBB0_1324:
	s_and_b32 s18, s24, 0xff
	s_cmp_lg_u32 s18, 0
	s_mov_b64 s[20:21], -1
	s_nop 0
	s_cbranch_scc0 .LBB0_1327
	s_mov_b64 s[22:23], -1
	s_and_b64 vcc, exec, s[20:21]
	s_cbranch_vccz .LBB0_1323
